# all decode units in the first S5 phase (waves 0 and 4), second S5 phase exactly two units per wave
# speedup vs baseline: 1.0010x; 1.0009x over previous
; __global__ void __launch_bounds__(512, 2) fwd(Params P) {
;     ...
;         for (int r2 = 0; r2 < NREP(15); ++r2) for (int id = blockIdx.x * 8 + wave; id < 4672; id += gridDim.x * 8) {
;             if (id < 2048 && (id & 7) == 0) { mlstm_decode_wave(P, shm + wave * S5_WL, id >> 3); continue; }
;             const int sidx = id < 2048 ? id - (id >> 3) - 1 : 1792 + (id - 2048);
;             if (sidx < 3904) s5_unit<0>(P, shm + wave * S5_WL, sidx); else s5_unit<2>(P, shm + wave * S5_WL, sidx - 3904); }
.LBB0_343:
	v_lshl_add_u32 v151, s94, 3, v215
	v_mov_b32_e32 v238, s94
	v_mul_u32_u24_e32 v241, 6, v238
	v_cmp_lt_u32_e32 vcc, 4, v215
	v_add_u32_e32 v242, -1, v215
	v_add_u32_e32 v243, -2, v215
	s_nop 1
	v_cndmask_b32_e32 v242, v242, v243, vcc
	v_add_u32_e32 v241, v241, v242
	v_add_u32_e32 v242, 0x100, v241
	v_add_u32_e32 v240, 0x700, v241
	v_add_u32_e32 v243, 0xd00, v241
	v_add_u32_e32 v244, 0xf00, v241
	v_cmp_gt_u32_e32 vcc, 0x340, v241
	v_mov_b32_e32 v239, 0x7fff
	s_nop 1
	v_cndmask_b32_e32 v244, v239, v244, vcc
	v_cmp_gt_u32_e32 vcc, 0x300, v241
	s_nop 1
	v_cndmask_b32_e32 v243, v244, v243, vcc
	v_and_b32_e32 v244, 3, v215
	v_cmp_eq_u32_e32 vcc, 0, v244
	v_lshlrev_b32_e32 v244, 9, v215
	v_lshl_add_u32 v244, v238, 3, v244
	v_lshrrev_b32_e32 v237, 2, v215
	v_lshl_add_u32 v237, v238, 1, v237
	v_add_u32_e32 v237, 0x1000, v237
	v_cndmask_b32_e32 v151, v242, v244, vcc
	v_cndmask_b32_e32 v240, v240, v237, vcc
	v_cndmask_b32_e32 v243, v243, v239, vcc
	v_mov_b32_e32 v241, 0
	s_movk_i32 s0, 0x1240
	v_cmp_gt_i32_e32 vcc, s0, v151
	s_barrier
	s_and_saveexec_b64 s[16:17], vcc
	s_cbranch_execz .LBB0_376
	s_movk_i32 s0, 0x4200
	v_mad_u32_u24 v153, v215, s0, 0
	v_add_u32_e32 v0, 0x1000, v153
	v_cndmask_b32_e64 v2, v0, v153, s[4:5]
	v_lshrrev_b32_e32 v0, 1, v146
	v_and_b32_e32 v150, 8, v0
	v_lshrrev_b32_e32 v1, 4, v146
	v_lshl_add_u32 v2, v150, 1, v2
	v_lshlrev_b32_e32 v3, 5, v147
	v_mov_b32_e32 v0, 0
	v_add_u32_e32 v183, v2, v3
	v_mul_u32_u24_e32 v2, 0x820, v1
	v_add3_u32 v212, v153, v2, v64
	v_and_b32_e32 v2, 48, v146
	v_lshlrev_b32_e32 v4, 3, v146
	v_mov_b32_e32 v5, v0
	v_readlane_b32 s52, v245, 34
	v_add3_u32 v213, v153, v3, v2
	v_mul_u32_u24_e32 v3, 0x110, v147
	v_add_u32_e32 v218, v153, v4
	v_lshl_add_u64 v[4:5], s[12:13], 0, v[4:5]
	s_mov_b64 s[0:1], 0x1e5cb000
	v_lshlrev_b32_e32 v158, 4, v146
	v_mov_b32_e32 v159, v0
	v_readlane_b32 s56, v245, 38
	v_readlane_b32 s57, v245, 39
	v_readlane_b32 s58, v245, 40
	v_readlane_b32 s59, v245, 41
	v_readlane_b32 s60, v245, 42
	v_readlane_b32 s61, v245, 43
	v_readlane_b32 s62, v245, 44
	v_readlane_b32 s63, v245, 45
	v_readlane_b32 s64, v245, 46
	v_readlane_b32 s65, v245, 47
	v_readlane_b32 s66, v245, 48
	v_readlane_b32 s67, v245, 49
	v_add3_u32 v216, v153, v3, v2
	v_lshl_add_u64 v[156:157], v[4:5], 0, s[0:1]
	v_readlane_b32 s72, v245, 18
	v_lshl_add_u64 v[4:5], s[66:67], 0, v[158:159]
	v_and_b32_e32 v3, 0xc0, v214
	v_readlane_b32 s56, v245, 2
	s_add_u32 s18, s12, 0x2100000
	v_readlane_b32 s73, v245, 19
	v_cmp_eq_u32_e64 s[6:7], 0, v3
	v_mov_b32_e32 v3, v0
	v_readlane_b32 s70, v245, 16
	v_readlane_b32 s71, v245, 17
	v_lshlrev_b32_e32 v152, 2, v1
	s_addc_u32 s19, s13, 0
	v_lshlrev_b32_e32 v1, 7, v1
	v_lshlrev_b32_e32 v154, 2, v146
	s_mov_b64 s[0:1], 0xc924040
	v_lshl_add_u64 v[166:167], s[70:71], 0, v[2:3]
	v_lshl_add_u64 v[168:169], s[72:73], 0, v[2:3]
	v_and_b32_e32 v2, 16, v146
	v_lshlrev_b32_e32 v6, 6, v147
	v_add3_u32 v217, v153, v1, v148
	v_sub_u32_e32 v1, 0, v154
	v_readlane_b32 s82, v245, 28
	v_readlane_b32 s83, v245, 29
	s_add_u32 s20, s12, 0x12dc2000
	v_readlane_b32 s53, v245, 35
	v_readlane_b32 s54, v245, 36
	v_readlane_b32 s55, v245, 37
	v_lshl_add_u64 v[164:165], v[4:5], 0, s[0:1]
	v_lshl_add_u64 v[2:3], s[12:13], 0, v[2:3]
	s_mov_b64 s[0:1], 0x458a000
	s_movk_i32 s25, 0x1000
	v_lshl_add_u32 v155, v146, 6, v153
	v_lshl_add_u64 v[160:161], s[46:47], 0, v[158:159]
	v_add_u32_e32 v219, v153, v158
	v_lshl_add_u64 v[162:163], s[82:83], 0, v[158:159]
	s_addc_u32 s21, s13, 0
	s_lshl_b32 s54, s96, 3
	v_lshl_add_u64 v[170:171], v[2:3], 0, s[0:1]
	s_mov_b64 s[22:23], 0
	s_mov_b32 s33, 0x3fb8aa3b
	s_mov_b32 s55, 0xc2ce8ed0
	s_mov_b32 s50, 0x42b17218
	s_brev_b32 s51, 18
	s_mov_b32 s93, 0xfe5163ab
	v_mov_b32_e32 v220, 0x3c0881c4
	v_mov_b32_e32 v221, 0xbab64f3b
	s_movk_i32 s89, 0x1f8
	v_lshlrev_b32_e32 v222, 2, v6
	s_movk_i32 s90, 0x4800
	s_movk_i32 s91, 0x7fff
	s_mov_b32 s92, 0x4524000
	s_mov_b32 s52, 0x4724000
	v_add_u32_e32 v223, v218, v1
	s_mov_b32 s53, 0x7060302
	s_mov_b32 s88, 0x88888889
	s_mov_b32 s24, 0x3d800000
	v_mov_b32_e32 v224, 0x3ecc95a3
	s_mov_b64 s[26:27], 0x8000
	v_mov_b32_e32 v225, 0x3727c5ac
	v_mov_b32_e32 v226, 0xffffff00
	v_mov_b32_e32 v227, 0x7f800000
	v_not_b32_e32 v228, 63
	v_not_b32_e32 v229, 31
	v_mov_b32_e32 v230, 0x7fc00000
	v_mov_b32_e32 v172, 0x3f317218
	v_mov_b32_e32 v231, 0xff800000
	v_readlane_b32 s74, v245, 20
	v_readlane_b32 s75, v245, 21
	v_readlane_b32 s76, v245, 22
	v_readlane_b32 s77, v245, 23
	v_readlane_b32 s78, v245, 24
	v_readlane_b32 s79, v245, 25
	v_readlane_b32 s80, v245, 26
	v_readlane_b32 s81, v245, 27
	v_readlane_b32 s84, v245, 30
	v_readlane_b32 s85, v245, 31
	v_readlane_b32 s86, v245, 32
	v_readlane_b32 s87, v245, 33
	v_readlane_b32 s57, v245, 3
	v_readlane_b32 s58, v245, 4
	v_readlane_b32 s59, v245, 5
	v_readlane_b32 s60, v245, 6
	v_readlane_b32 s61, v245, 7
	v_readlane_b32 s62, v245, 8
	v_readlane_b32 s63, v245, 9
	v_readlane_b32 s64, v245, 10
	v_readlane_b32 s65, v245, 11
	v_readlane_b32 s66, v245, 12
	v_readlane_b32 s67, v245, 13
	v_readlane_b32 s68, v245, 14
	v_readlane_b32 s69, v245, 15
	s_branch .LBB0_347

; __device__ __forceinline__ void s5_setup(const Params& P, int g, int p, float& ar, float& ai, float (&Br)[16], float (&Bi)[16]) {
;     ...
;     const float lre = P.in[10][gp], lim = P.in[11][gp], dt = expf(P.in[12][gp]);
;     const float zr = lre * dt, zi = lim * dt; const float er = expf(zr); float sn, cs; sincosf(zi, &sn, &cs);
;     ar = er * cs; ai = er * sn;
; __global__ void __launch_bounds__(512, 2) fwd(Params P) {
;     ...
;         for (int r2 = 0; r2 < NREP(15); ++r2) for (int id = blockIdx.x * 8 + wave; id < 4672; id += gridDim.x * 8) {
;             if (id < 2048 && (id & 7) == 0) { mlstm_decode_wave(P, shm + wave * S5_WL, id >> 3); continue; }
;             const int sidx = id < 2048 ? id - (id >> 3) - 1 : 1792 + (id - 2048);
;             if (sidx < 3904) s5_unit<0>(P, shm + wave * S5_WL, sidx); else s5_unit<2>(P, shm + wave * S5_WL, sidx - 3904); }
.LBB0_346:
	s_or_b64 exec, exec, s[0:1]
	v_add_u32_e32 v241, 1, v241
	v_cmp_eq_u32_e32 vcc, 1, v241
	s_nop 1
	v_cndmask_b32_e32 v151, v243, v240, vcc
	v_cmp_lt_u32_e32 vcc, 2, v241
	s_nop 1
	v_cndmask_b32_e32 v151, v151, v239, vcc
	s_movk_i32 s0, 0x123f
	v_cmp_lt_i32_e32 vcc, s0, v151
	s_or_b64 s[22:23], vcc, s[22:23]
	s_andn2_b64 exec, exec, s[22:23]
	s_cbranch_execz .LBB0_376
.LBB0_347:
	s_movk_i32 s0, 0x1000
	v_cmp_gt_i32_e32 vcc, s0, v151
	s_and_b64 s[0:1], vcc, s[6:7]
	s_xor_b64 s[0:1], s[0:1], -1
	v_ashrrev_i32_e32 v174, 3, v151
	s_and_saveexec_b64 s[8:9], s[0:1]
	s_xor_b64 s[28:29], exec, s[8:9]
	s_cbranch_execz .LBB0_370
	v_not_b32_e32 v1, v174
	v_mov_b32_e32 v1, v226
	v_add_u32_e32 v3, v1, v151
	s_movk_i32 s0, 0xf3f
	v_cmp_lt_i32_e32 vcc, s0, v3
	s_and_saveexec_b64 s[0:1], vcc
	s_xor_b64 s[30:31], exec, s[0:1]
	s_cbranch_execz .LBB0_356
	v_and_b32_e32 v1, 63, v3
	v_lshl_or_b32 v2, v1, 6, v146
	v_readlane_b32 s56, v245, 2
	v_lshlrev_b32_e32 v4, 2, v2
	v_readlane_b32 s64, v245, 10
	v_readlane_b32 s65, v245, 11
	v_readlane_b32 s60, v245, 6
	v_readlane_b32 s61, v245, 7
	v_readlane_b32 s62, v245, 8
	v_readlane_b32 s63, v245, 9
	s_nop 0
	global_load_dword v5, v4, s[64:65]
	s_nop 2
	global_load_dword v35, v4, s[62:63]
	global_load_dword v34, v4, s[60:61]
	v_readlane_b32 s57, v245, 3
	v_readlane_b32 s58, v245, 4
	v_readlane_b32 s59, v245, 5
	v_readlane_b32 s66, v245, 12
	v_readlane_b32 s67, v245, 13
	v_readlane_b32 s68, v245, 14
	v_readlane_b32 s69, v245, 15
	v_readlane_b32 s70, v245, 16
	v_readlane_b32 s71, v245, 17
	s_waitcnt vmcnt(2)
	v_mul_f32_e32 v4, 0x3fb8aa3b, v5
	v_fma_f32 v6, v5, s33, -v4
	v_rndne_f32_e32 v7, v4
	v_fmac_f32_e32 v6, 0x32a5705f, v5
	v_sub_f32_e32 v4, v4, v7
	v_add_f32_e32 v4, v4, v6
	v_cvt_i32_f32_e32 v7, v7
	v_exp_f32_e32 v4, v4
	v_cmp_ngt_f32_e32 vcc, s55, v5
	v_ldexp_f32 v4, v4, v7
	s_nop 0
	v_cndmask_b32_e32 v4, 0, v4, vcc
	v_cmp_nlt_f32_e32 vcc, s50, v5
	s_nop 1
	v_cndmask_b32_e32 v6, v227, v4, vcc
	s_waitcnt vmcnt(1)
	v_mul_f32_e32 v4, v35, v6
	v_and_b32_e32 v5, 0x7fffffff, v4
	v_cmp_nlt_f32_e64 s[0:1], |v4|, s51
	s_and_saveexec_b64 s[8:9], s[0:1]
	s_xor_b64 s[34:35], exec, s[8:9]
	s_cbranch_execz .LBB0_351
	v_lshrrev_b32_e32 v7, 23, v5
	v_add_u32_e32 v7, 0xffffff88, v7
	v_cmp_lt_u32_e32 vcc, 63, v7
	v_mov_b32_e32 v11, v0
	v_mov_b32_e32 v13, v0
	v_cndmask_b32_e32 v8, 0, v228, vcc
	v_add_u32_e32 v7, v8, v7
	v_cmp_lt_u32_e64 s[0:1], 31, v7
	v_mov_b32_e32 v15, v0
	v_mov_b32_e32 v17, v0
	v_cndmask_b32_e64 v8, 0, v229, s[0:1]
	v_add_u32_e32 v7, v8, v7
	v_cmp_lt_u32_e64 s[8:9], 31, v7
	v_mov_b32_e32 v19, v0
	v_mov_b32_e32 v21, v0
	v_cndmask_b32_e64 v8, 0, v229, s[8:9]
	v_add_u32_e32 v7, v8, v7
	v_and_b32_e32 v8, 0x7fffff, v5
	v_or_b32_e32 v22, 0x800000, v8
	v_mad_u64_u32 v[8:9], s[10:11], v22, s93, 0
	v_mov_b32_e32 v10, v9
	s_mov_b32 s10, 0x3c439041
	v_mad_u64_u32 v[10:11], s[10:11], v22, s10, v[10:11]
	v_mov_b32_e32 v12, v11
	s_mov_b32 s10, 0xdb629599
	v_mad_u64_u32 v[12:13], s[10:11], v22, s10, v[12:13]
	v_mov_b32_e32 v14, v13
	s_mov_b32 s10, 0xf534ddc0
	v_mad_u64_u32 v[14:15], s[10:11], v22, s10, v[14:15]
	v_mov_b32_e32 v16, v15
	s_mov_b32 s10, 0xfc2757d1
	v_mad_u64_u32 v[16:17], s[10:11], v22, s10, v[16:17]
	v_mov_b32_e32 v18, v17
	s_mov_b32 s10, 0x4e441529
	v_mad_u64_u32 v[18:19], s[10:11], v22, s10, v[18:19]
	v_mov_b32_e32 v20, v19
	s_mov_b32 s10, 0xa2f9836e
	v_mad_u64_u32 v[20:21], s[10:11], v22, s10, v[20:21]
	v_cndmask_b32_e32 v9, v18, v14, vcc
	v_cndmask_b32_e32 v11, v20, v16, vcc
	v_cndmask_b32_e32 v15, v21, v18, vcc
	v_cndmask_b32_e64 v13, v11, v9, s[0:1]
	v_cndmask_b32_e64 v11, v15, v11, s[0:1]
	v_cndmask_b32_e32 v15, v16, v12, vcc
	v_cndmask_b32_e64 v9, v9, v15, s[0:1]
	v_sub_u32_e32 v16, 32, v7
	v_cmp_eq_u32_e64 s[10:11], 0, v7
	v_cndmask_b32_e32 v7, v14, v10, vcc
	v_cndmask_b32_e64 v11, v11, v13, s[8:9]
	v_cndmask_b32_e64 v13, v13, v9, s[8:9]
	v_cndmask_b32_e64 v10, v15, v7, s[0:1]
	v_alignbit_b32 v17, v11, v13, v16
	v_cndmask_b32_e64 v9, v9, v10, s[8:9]
	v_cndmask_b32_e64 v11, v17, v11, s[10:11]
	v_alignbit_b32 v14, v13, v9, v16
	v_cndmask_b32_e32 v8, v12, v8, vcc
	v_cndmask_b32_e64 v13, v14, v13, s[10:11]
	v_bfe_u32 v17, v11, 29, 1
	v_cndmask_b32_e64 v7, v7, v8, s[0:1]
	v_alignbit_b32 v14, v11, v13, 30
	v_sub_u32_e32 v18, 0, v17
	v_cndmask_b32_e64 v7, v10, v7, s[8:9]
	v_xor_b32_e32 v14, v14, v18
	v_alignbit_b32 v8, v9, v7, v16
	v_cndmask_b32_e64 v8, v8, v9, s[10:11]
	v_ffbh_u32_e32 v10, v14
	v_alignbit_b32 v9, v13, v8, 30
	v_min_u32_e32 v10, 32, v10
	v_alignbit_b32 v7, v8, v7, 30
	v_xor_b32_e32 v9, v9, v18
	v_sub_u32_e32 v12, 31, v10
	v_xor_b32_e32 v7, v7, v18
	v_alignbit_b32 v13, v14, v9, v12
	v_alignbit_b32 v7, v9, v7, v12
	v_alignbit_b32 v8, v13, v7, 9
	v_ffbh_u32_e32 v9, v8
	v_min_u32_e32 v9, 32, v9
	v_lshrrev_b32_e32 v15, 29, v11
	v_not_b32_e32 v12, v9
	v_alignbit_b32 v7, v8, v7, v12
	v_lshlrev_b32_e32 v8, 31, v15
	v_or_b32_e32 v12, 0x33000000, v8
	v_add_lshl_u32 v9, v9, v10, 23
	v_lshrrev_b32_e32 v7, 9, v7
	v_sub_u32_e32 v9, v12, v9
	v_or_b32_e32 v8, 0.5, v8
	v_lshlrev_b32_e32 v10, 23, v10
	v_or_b32_e32 v7, v9, v7
	v_lshrrev_b32_e32 v9, 9, v13
	v_sub_u32_e32 v8, v8, v10
	v_or_b32_e32 v8, v9, v8
	v_mul_f32_e32 v9, 0x3fc90fda, v8
	s_mov_b32 s0, 0x3fc90fda
	v_fma_f32 v10, v8, s0, -v9
	v_fmac_f32_e32 v10, 0x33a22168, v8
	v_fmac_f32_e32 v10, 0x3fc90fda, v7
	v_lshrrev_b32_e32 v8, 30, v11
	v_add_f32_e32 v7, v9, v10
	v_add_u32_e32 v8, v17, v8

; __global__ void __launch_bounds__(512, 2) fwd(Params P) {
;     ...
;         for (int r2 = 0; r2 < NREP(13); ++r2) for (int id = blockIdx.x * 8 + wave; id < 4352; id += gridDim.x * 8) {
;             if (id < 2048 && (id & 7) == 0) { mlstm_decode_wave(P, shm + wave * S5_WL, 256 + (id >> 3)); continue; }
;             s5_unit<1>(P, shm + wave * S5_WL, id < 2048 ? id - (id >> 3) - 1 : 1792 + (id - 2048)); }
.LBB0_439:
	s_or_b64 exec, exec, s[4:5]
	v_lshl_add_u32 v145, s94, 3, v215
	v_add_u32_e32 v145, 0x100, v145
	s_movk_i32 s0, 0x1100
	v_cmp_gt_i32_e32 vcc, s0, v145
	s_and_saveexec_b64 s[16:17], vcc
	s_cbranch_execz .LBB0_469
	s_movk_i32 s0, 0x4200
	v_mad_u32_u24 v153, v215, s0, 0
	v_and_b32_e32 v144, 63, v214
	v_add_u32_e32 v0, 0x1000, v153
	s_add_u32 s18, s12, 0x4542000
	v_cmp_gt_u32_e64 s[2:3], 32, v144
	s_addc_u32 s19, s13, 0
	v_and_b32_e32 v157, 15, v214
	v_cndmask_b32_e64 v2, v0, v153, s[2:3]
	v_lshrrev_b32_e32 v0, 1, v214
	v_and_b32_e32 v0, 8, v0
	v_mov_b32_e32 v147, 0
	s_add_u32 s20, s12, 0x1e5cb000
	v_bfe_u32 v1, v214, 4, 2
	v_lshlrev_b32_e32 v3, 1, v0
	v_lshlrev_b32_e32 v4, 5, v157
	s_addc_u32 s21, s13, 0
	v_lshlrev_b32_e32 v148, 3, v144
	v_mov_b32_e32 v149, v147
	v_add3_u32 v216, v2, v3, v4
	v_lshl_add_u64 v[150:151], s[20:21], 0, v[148:149]
	v_mul_u32_u24_e32 v2, 0x820, v1
	v_lshlrev_b32_e32 v149, 2, v157
	v_lshlrev_b32_e32 v146, 1, v157
	v_add3_u32 v217, v153, v2, v149
	v_lshl_add_u64 v[2:3], s[12:13], 0, v[146:147]
	s_mov_b64 s[0:1], 0x2100000
	v_add_u32_e32 v5, v153, v146
	v_lshl_add_u64 v[154:155], v[2:3], 0, s[0:1]
	v_mul_u32_u24_e32 v2, 30, v157
	v_and_b32_e32 v146, 48, v214
	v_readlane_b32 s52, v245, 34
	v_add3_u32 v218, v5, v2, v146
	v_mul_u32_u24_e32 v2, 0x110, v157
	v_lshlrev_b32_e32 v158, 4, v144
	v_mov_b32_e32 v159, v147
	v_readlane_b32 s53, v245, 35
	v_readlane_b32 s54, v245, 36
	v_readlane_b32 s55, v245, 37
	v_readlane_b32 s56, v245, 38
	v_readlane_b32 s57, v245, 39
	v_readlane_b32 s58, v245, 40
	v_readlane_b32 s59, v245, 41
	v_readlane_b32 s60, v245, 42
	v_readlane_b32 s61, v245, 43
	v_readlane_b32 s62, v245, 44
	v_readlane_b32 s63, v245, 45
	v_readlane_b32 s64, v245, 46
	v_readlane_b32 s65, v245, 47
	v_readlane_b32 s66, v245, 48
	v_readlane_b32 s67, v245, 49
	v_add3_u32 v219, v153, v2, v146
	v_readlane_b32 s68, v245, 18
	v_lshl_add_u64 v[2:3], s[66:67], 0, v[158:159]
	v_readlane_b32 s52, v245, 2
	s_add_u32 s22, s12, 0x4500000
	v_readlane_b32 s69, v245, 19
	s_mov_b64 s[0:1], 0xc924040
	v_readlane_b32 s66, v245, 16
	v_readlane_b32 s67, v245, 17
	s_addc_u32 s23, s13, 0
	v_lshl_add_u64 v[164:165], v[2:3], 0, s[0:1]
	v_and_b32_e32 v2, 0x1c0, v214
	v_lshl_add_u64 v[166:167], s[66:67], 0, v[146:147]
	v_lshl_add_u64 v[168:169], s[68:69], 0, v[146:147]
	v_and_b32_e32 v146, 16, v214
	v_lshlrev_b32_e32 v156, 2, v144
	s_add_u32 s24, s12, 0x12dc2000
	s_mov_b64 s[6:7], 0
	v_lshl_add_u64 v[2:3], s[12:13], 0, v[146:147]
	s_mov_b64 s[0:1], 0x458a000
	v_lshlrev_b32_e32 v152, 2, v1
	v_lshlrev_b32_e32 v4, 6, v157
	v_lshlrev_b32_e32 v1, 7, v1
	v_add_u32_e32 v220, v153, v156
	v_mul_u32_u24_e32 v6, 12, v144
	v_readlane_b32 s78, v245, 28
	v_readlane_b32 s79, v245, 29
	s_addc_u32 s25, s13, 0
	v_lshl_add_u64 v[170:171], v[2:3], 0, s[0:1]
	s_lshl_b32 s0, s94, 3
	s_movk_i32 s29, 0x1000
	v_lshl_add_u32 v185, v144, 6, v153
	v_lshl_add_u64 v[160:161], s[46:47], 0, v[158:159]
	v_lshl_add_u64 v[162:163], s[78:79], 0, v[158:159]
	v_cmp_eq_u32_e64 s[4:5], 0, v144
	s_lshl_b32 s33, s96, 3
	v_add_u16_e32 v221, s0, v215
	v_add_u16_e32 v221, 0x100, v221
	s_mov_b64 s[26:27], 0
	s_mov_b32 s42, 0x3fb8aa3b
	s_mov_b32 s43, 0xc2ce8ed0
	s_mov_b32 s46, 0x42b17218
	v_mov_b32_e32 v222, 0x3c0881c4
	v_mov_b32_e32 v223, 0xbab64f3b
	v_lshlrev_b32_e32 v224, 2, v4
	s_movk_i32 s47, 0x7fff
	s_movk_i32 s50, 0x4800
	v_lshlrev_b32_e32 v172, 1, v0
	s_mov_b32 s51, 0x7060302
	v_add_u32_e32 v225, v220, v6
	v_mov_b32_e32 v226, 0x3ecc95a3
	v_mov_b32_e32 v227, 0x3727c5ac
	v_mov_b32_e32 v228, 0xffffff00
	v_mov_b32_e32 v229, 0x7f800000
	v_not_b32_e32 v230, 63
	v_not_b32_e32 v231, 31
	v_mov_b32_e32 v232, 0x7fc00000
	v_add_u32_e32 v233, v5, v1
	v_mov_b32_e32 v174, 0x3f317218
	v_mov_b32_e32 v234, 0xff800000
	s_mov_b32 s28, 0x3d800000
	s_mov_b64 s[30:31], 0x8000
	v_readlane_b32 s70, v245, 20
	v_readlane_b32 s71, v245, 21
	v_readlane_b32 s72, v245, 22
	v_readlane_b32 s73, v245, 23
	v_readlane_b32 s74, v245, 24
	v_readlane_b32 s75, v245, 25
	v_readlane_b32 s76, v245, 26
	v_readlane_b32 s77, v245, 27
	v_readlane_b32 s80, v245, 30
	v_readlane_b32 s81, v245, 31
	v_readlane_b32 s82, v245, 32
	v_readlane_b32 s83, v245, 33
	v_readlane_b32 s53, v245, 3
	v_readlane_b32 s54, v245, 4
	v_readlane_b32 s55, v245, 5
	v_readlane_b32 s56, v245, 6
	v_readlane_b32 s57, v245, 7
	v_readlane_b32 s58, v245, 8
	v_readlane_b32 s59, v245, 9
	v_readlane_b32 s60, v245, 10
	v_readlane_b32 s61, v245, 11
	v_readlane_b32 s62, v245, 12
	v_readlane_b32 s63, v245, 13
	v_readlane_b32 s64, v245, 14
	v_readlane_b32 s65, v245, 15
	s_branch .LBB0_443

; __device__ __forceinline__ void s5_setup(const Params& P, int g, int p, float& ar, float& ai, float (&Br)[16], float (&Bi)[16]) {
;     ...
;     const float lre = P.in[10][gp], lim = P.in[11][gp], dt = expf(P.in[12][gp]);
;     const float zr = lre * dt, zi = lim * dt; const float er = expf(zr); float sn, cs; sincosf(zi, &sn, &cs);
;     ar = er * cs; ai = er * sn;
; __global__ void __launch_bounds__(512, 2) fwd(Params P) {
;     ...
;         for (int r2 = 0; r2 < NREP(13); ++r2) for (int id = blockIdx.x * 8 + wave; id < 4352; id += gridDim.x * 8) {
;             if (id < 2048 && (id & 7) == 0) { mlstm_decode_wave(P, shm + wave * S5_WL, 256 + (id >> 3)); continue; }
;             s5_unit<1>(P, shm + wave * S5_WL, id < 2048 ? id - (id >> 3) - 1 : 1792 + (id - 2048)); }
.LBB0_443:
	s_movk_i32 s0, 0x800
	v_cmp_gt_i32_e32 vcc, s0, v145
	s_and_b64 s[0:1], vcc, s[6:7]
	s_xor_b64 s[0:1], s[0:1], -1
	v_ashrrev_i32_e32 v176, 3, v145
	s_and_saveexec_b64 s[8:9], s[0:1]
	s_xor_b64 s[34:35], exec, s[8:9]
	s_cbranch_execz .LBB0_464
	v_not_b32_e32 v0, v176
	v_mov_b32_e32 v69, v228
	s_waitcnt vmcnt(3)
	v_add_u32_e32 v63, v69, v145
	v_and_b32_e32 v66, 63, v63
	v_lshl_or_b32 v34, v66, 6, v144
	v_readlane_b32 s52, v245, 2
	v_lshlrev_b32_e32 v0, 2, v34
	v_readlane_b32 s60, v245, 10
	v_readlane_b32 s61, v245, 11
	v_readlane_b32 s56, v245, 6
	v_readlane_b32 s57, v245, 7
	v_readlane_b32 s58, v245, 8
	v_readlane_b32 s59, v245, 9
	s_nop 0
	global_load_dword v1, v0, s[60:61]
	s_nop 2
	global_load_dword v33, v0, s[58:59]
	global_load_dword v32, v0, s[56:57]
	s_brev_b32 s0, 18
	v_readlane_b32 s53, v245, 3
	v_readlane_b32 s54, v245, 4
	v_readlane_b32 s55, v245, 5
	v_readlane_b32 s62, v245, 12
	v_readlane_b32 s63, v245, 13
	v_readlane_b32 s64, v245, 14
	v_readlane_b32 s65, v245, 15
	v_readlane_b32 s66, v245, 16
	v_readlane_b32 s67, v245, 17
	s_waitcnt vmcnt(2)
	v_mul_f32_e32 v0, 0x3fb8aa3b, v1
	v_fma_f32 v2, v1, s42, -v0
	v_rndne_f32_e32 v3, v0
	v_fmac_f32_e32 v2, 0x32a5705f, v1
	v_sub_f32_e32 v0, v0, v3
	v_add_f32_e32 v0, v0, v2
	v_cvt_i32_f32_e32 v3, v3
	v_exp_f32_e32 v0, v0
	v_cmp_ngt_f32_e32 vcc, s43, v1
	v_ldexp_f32 v0, v0, v3
	s_nop 0
	v_cndmask_b32_e32 v0, 0, v0, vcc
	v_cmp_nlt_f32_e32 vcc, s46, v1
	s_nop 1
	v_cndmask_b32_e32 v1, v229, v0, vcc
	s_waitcnt vmcnt(1)
	v_mul_f32_e32 v35, v33, v1
	v_and_b32_e32 v0, 0x7fffffff, v35
	v_cmp_nlt_f32_e64 s[0:1], |v35|, s0
	s_and_saveexec_b64 s[8:9], s[0:1]
	s_xor_b64 s[40:41], exec, s[8:9]
	s_cbranch_execz .LBB0_446
	v_lshrrev_b32_e32 v2, 23, v0
	v_add_u32_e32 v2, 0xffffff88, v2
	v_cmp_lt_u32_e32 vcc, 63, v2
	s_mov_b32 s10, 0xfe5163ab
	s_nop 0
	v_cndmask_b32_e32 v3, 0, v230, vcc
	v_add_u32_e32 v2, v3, v2
	v_cmp_lt_u32_e64 s[0:1], 31, v2
	s_nop 1
	v_cndmask_b32_e64 v3, 0, v231, s[0:1]
	v_add_u32_e32 v2, v3, v2
	v_cmp_lt_u32_e64 s[8:9], 31, v2
	s_nop 1
	v_cndmask_b32_e64 v3, 0, v231, s[8:9]
	v_add_u32_e32 v16, v3, v2
	v_and_b32_e32 v2, 0x7fffff, v0
	v_or_b32_e32 v14, 0x800000, v2
	v_mad_u64_u32 v[2:3], s[10:11], v14, s10, 0
	v_mov_b32_e32 v146, v3
	s_mov_b32 s10, 0x3c439041
	v_mad_u64_u32 v[4:5], s[10:11], v14, s10, v[146:147]
	v_mov_b32_e32 v146, v5
	s_mov_b32 s10, 0xdb629599
	v_mad_u64_u32 v[6:7], s[10:11], v14, s10, v[146:147]
	v_mov_b32_e32 v146, v7
	s_mov_b32 s10, 0xf534ddc0
	v_mad_u64_u32 v[8:9], s[10:11], v14, s10, v[146:147]
	v_mov_b32_e32 v146, v9
	s_mov_b32 s10, 0xfc2757d1
	v_mad_u64_u32 v[10:11], s[10:11], v14, s10, v[146:147]
	v_mov_b32_e32 v146, v11
	s_mov_b32 s10, 0x4e441529
	v_mad_u64_u32 v[12:13], s[10:11], v14, s10, v[146:147]
	v_mov_b32_e32 v146, v13
	s_mov_b32 s10, 0xa2f9836e
	v_mad_u64_u32 v[14:15], s[10:11], v14, s10, v[146:147]
	v_cndmask_b32_e32 v3, v12, v8, vcc
	v_cndmask_b32_e32 v5, v14, v10, vcc
	v_cndmask_b32_e32 v9, v15, v12, vcc
	v_cndmask_b32_e64 v7, v5, v3, s[0:1]
	v_cndmask_b32_e64 v5, v9, v5, s[0:1]
	v_cndmask_b32_e32 v9, v10, v6, vcc
	v_cndmask_b32_e64 v3, v3, v9, s[0:1]
	v_cndmask_b32_e32 v4, v8, v4, vcc
	v_cndmask_b32_e64 v5, v5, v7, s[8:9]
	v_cndmask_b32_e64 v7, v7, v3, s[8:9]
	v_sub_u32_e32 v10, 32, v16
	v_cndmask_b32_e64 v8, v9, v4, s[0:1]
	v_alignbit_b32 v11, v5, v7, v10
	v_cmp_eq_u32_e64 s[10:11], 0, v16
	v_cndmask_b32_e64 v3, v3, v8, s[8:9]
	v_alignbit_b32 v9, v7, v3, v10
	v_cndmask_b32_e64 v5, v11, v5, s[10:11]
	v_cndmask_b32_e32 v2, v6, v2, vcc
	v_cndmask_b32_e64 v7, v9, v7, s[10:11]
	v_bfe_u32 v12, v5, 29, 1
	v_cndmask_b32_e64 v2, v4, v2, s[0:1]
	v_alignbit_b32 v9, v5, v7, 30
	v_sub_u32_e32 v13, 0, v12
	v_cndmask_b32_e64 v2, v8, v2, s[8:9]
	v_xor_b32_e32 v9, v9, v13
	v_alignbit_b32 v4, v3, v2, v10
	v_cndmask_b32_e64 v3, v4, v3, s[10:11]
	v_ffbh_u32_e32 v6, v9
	v_alignbit_b32 v4, v7, v3, 30
	v_min_u32_e32 v6, 32, v6
	v_alignbit_b32 v2, v3, v2, 30
	v_xor_b32_e32 v4, v4, v13
	v_sub_u32_e32 v7, 31, v6
	v_xor_b32_e32 v2, v2, v13
	v_alignbit_b32 v8, v9, v4, v7
	v_alignbit_b32 v2, v4, v2, v7
	v_alignbit_b32 v3, v8, v2, 9
	v_ffbh_u32_e32 v4, v3
	v_min_u32_e32 v4, 32, v4
	v_lshrrev_b32_e32 v11, 29, v5
	v_not_b32_e32 v7, v4
	v_alignbit_b32 v2, v3, v2, v7
	v_lshlrev_b32_e32 v3, 31, v11
	v_or_b32_e32 v7, 0x33000000, v3
	v_add_lshl_u32 v4, v4, v6, 23
	v_lshrrev_b32_e32 v2, 9, v2
	v_sub_u32_e32 v4, v7, v4
	v_or_b32_e32 v3, 0.5, v3
	v_lshlrev_b32_e32 v6, 23, v6
	v_or_b32_e32 v2, v4, v2
	v_lshrrev_b32_e32 v4, 9, v8
	v_sub_u32_e32 v3, v3, v6
	v_or_b32_e32 v3, v4, v3
	v_mul_f32_e32 v4, 0x3fc90fda, v3
	s_mov_b32 s0, 0x3fc90fda
	v_fma_f32 v6, v3, s0, -v4
	v_fmac_f32_e32 v6, 0x33a22168, v3
	v_fmac_f32_e32 v6, 0x3fc90fda, v2
	v_lshrrev_b32_e32 v2, 30, v5
	v_add_f32_e32 v36, v4, v6
	v_add_u32_e32 v2, v12, v2
